# v65 + guards: early P1b call and the shortened P1b phase only when the grid is 256 workgroups
# baseline (speedup 1.0000x reference)
.Lp1be_chk:
	s_cmpk_lg_u32 s80, 0x100
	s_cbranch_scc1 .LBB0_495
	s_cmpk_lt_u32 s83, 0x80
	s_cbranch_scc1 .LBB0_495
	s_waitcnt vmcnt(0) lgkmcnt(0)
	v_readlane_b32 s86, v254, 50
	v_readlane_b32 s87, v254, 51
	v_readlane_b32 s74, v255, 1
	v_readlane_b32 s78, v254, 62
	v_readlane_b32 s90, v254, 54
	v_readlane_b32 s92, v254, 52
	v_readlane_b32 s75, v255, 2
	v_readlane_b32 s79, v254, 63
	v_readlane_b32 s77, v254, 61
	v_readlane_b32 s82, v254, 58
	v_readlane_b32 s91, v254, 55
	v_readlane_b32 s93, v254, 53
	v_and_b32_e32 v0, 63, v179
	v_min_u32_e32 v0, 8, v0
	v_lshlrev_b32_e32 v0, 5, v0
	s_add_u32 s100, s74, 0x80000
	s_addc_u32 s101, s75, 0
	s_movk_i32 s99, 0x200

.LBB0_547:
	s_or_b64 exec, exec, s[0:1]
	s_mov_b32 s98, 0
	s_movk_i32 s99, 0x600
	s_movk_i32 s100, 0x5ff
	s_cmpk_lg_u32 s80, 0x100
	s_cbranch_scc1 .Lp1be_entry
	s_movk_i32 s99, 0x400
	s_movk_i32 s100, 0x3ff
